# GQA loop: wave-uniform fast path skipping the per-element window-mask code for key tiles fully inside the window (adds to v20)
# speedup vs baseline: 1.0174x; 1.0002x over previous
; #define SBAR() __builtin_amdgcn_sched_barrier(0)
; __device__ __forceinline__ int crow(int r, int hi) { return (r & 3) + 8 * (r >> 2) + 4 * hi; }
; #define QKT(P0, P1, BUF) qkt<DQK, QL>(P0, P1, shm + K_OFF + (BUF) * SHM_K, qr, qlds, kofs, negM)
; template <bool GM>
; __device__ __forceinline__ void partialSM(f32x16& p0, f32x16& p1, bool mask, int kbase, int L, int qpos, int hi) {
;   if (mask) {
; #pragma unroll
;     for (int r = 0; r < 16; ++r) {
;       int k = kbase + crow(r, hi);
;       asm volatile("" : "+v"(k) : "v"(p0[r]));
;       bool ok = k < L;
;       if (GM) ok = ok && (k < 16 || abs(qpos - k) <= 128);
;       p0[r] = ok ? p0[r] : -1e30f;
;       int k2 = k + 32;
;       asm volatile("" : "+v"(k2) : "v"(p1[r]));
;       bool ok2 = k2 < L;
;       if (GM) ok2 = ok2 && (k2 < 16 || abs(qpos - k2) <= 128);
;       p1[r] = ok2 ? p1[r] : -1e30f;
;     }
;   }
;     ...
;   for (; j + 1 < NT; j += 2) {
;     SBAR();
;     if constexpr (ONEP) { finishSM(pA0, pA1, l_reg, pa0, pa1, pa2, pa3); SBAR(); QKT(pB0, pB1, 1); }
;     else { QKT(pB0, pB1, 1); finishSM(pA0, pA1, l_reg, pa0, pa1, pa2, pa3); }
;     SBAR();
;     SLOAD(TKEY(j + 1), 0); SBAR();
;     pv_all<NCB>(o, vb0, pa0, pa1, pa2, pa3);
;     kb = TKEY(j);
;     partialSM<GM>(pB0, pB1, NEEDMASK(kb), kb, L, qpos, hi);
.LBB0_650:
	ds_read_b128 v[40:43], v150 offset:40960
	ds_read_b128 v[158:161], v150 offset:45056
	s_waitcnt vmcnt(0)
	v_mov_b64_e32 v[110:111], s[18:19]
	v_mov_b64_e32 v[108:109], s[16:17]
	v_mov_b64_e32 v[106:107], s[14:15]
	v_mov_b64_e32 v[104:105], s[12:13]
	v_mov_b64_e32 v[102:103], s[10:11]
	v_mov_b64_e32 v[100:101], s[8:9]
	v_mov_b64_e32 v[98:99], s[6:7]
	v_mov_b64_e32 v[96:97], s[4:5]
	s_waitcnt lgkmcnt(1)
	s_nop 0
	v_mfma_f32_32x32x16_bf16 v[56:71], v[40:43], v[124:127], v[96:111]
	s_waitcnt lgkmcnt(0)
	v_mfma_f32_32x32x16_bf16 v[40:55], v[158:161], v[124:127], v[96:111]
	s_nop 6
	ds_read_b128 v[96:99], v148 offset:40960
	ds_read_b128 v[100:103], v148 offset:45056
	s_waitcnt lgkmcnt(1)
	v_mfma_f32_32x32x16_bf16 v[56:71], v[96:99], v[120:123], v[56:71]
	s_waitcnt lgkmcnt(0)
	v_mfma_f32_32x32x16_bf16 v[40:55], v[100:103], v[120:123], v[40:55]
	ds_read_b128 v[96:99], v147 offset:40960
	ds_read_b128 v[100:103], v147 offset:45056
	s_waitcnt lgkmcnt(1)
	v_mfma_f32_32x32x16_bf16 v[56:71], v[96:99], v[116:119], v[56:71]
	s_waitcnt lgkmcnt(0)
	v_mfma_f32_32x32x16_bf16 v[40:55], v[100:103], v[116:119], v[40:55]
	ds_read_b128 v[96:99], v146 offset:40960
	ds_read_b128 v[100:103], v146 offset:45056
	s_waitcnt lgkmcnt(1)
	v_mfma_f32_32x32x16_bf16 v[56:71], v[96:99], v[112:115], v[56:71]
	v_exp_f32_e32 v96, v32
	v_add_f32_e32 v32, 0, v90
	v_add_f32_e32 v32, v91, v32
	v_add_f32_e32 v32, v88, v32
	v_add_f32_e32 v32, v87, v32
	v_add_f32_e32 v32, v86, v32
	v_add_f32_e32 v32, v85, v32
	v_add_f32_e32 v32, v82, v32
	v_add_f32_e32 v32, v81, v32
	v_add_f32_e32 v32, v74, v32
	v_add_f32_e32 v32, v75, v32
	v_add_f32_e32 v32, v76, v32
	v_add_f32_e32 v32, v77, v32
	v_add_f32_e32 v32, v78, v32
	v_exp_f32_e32 v97, v33
	v_add_f32_e32 v32, v79, v32
	v_exp_f32_e32 v98, v34
	v_add_f32_e32 v32, v80, v32
	v_exp_f32_e32 v99, v35
	v_add_f32_e32 v32, v83, v32
	s_waitcnt lgkmcnt(0)
	v_mfma_f32_32x32x16_bf16 v[40:55], v[100:103], v[112:115], v[40:55]
	v_exp_f32_e32 v100, v36
	v_add_f32_e32 v32, v96, v32
	v_exp_f32_e32 v101, v37
	v_add_f32_e32 v32, v97, v32
	v_exp_f32_e32 v102, v38
	v_add_f32_e32 v32, v98, v32
	v_exp_f32_e32 v103, v39
	v_add_f32_e32 v32, v99, v32
	v_exp_f32_e32 v36, v72
	v_add_f32_e32 v32, v100, v32
	v_exp_f32_e32 v37, v73
	v_add_f32_e32 v32, v101, v32
	v_exp_f32_e32 v38, v84
	v_add_f32_e32 v32, v102, v32
	v_exp_f32_e32 v39, v89
	v_add_f32_e32 v32, v103, v32
	v_exp_f32_e32 v72, v92
	v_add_f32_e32 v32, v36, v32
	v_exp_f32_e32 v73, v93
	v_add_f32_e32 v32, v37, v32
	v_exp_f32_e32 v84, v94
	v_add_f32_e32 v32, v38, v32
	v_exp_f32_e32 v89, v95
	v_add_f32_e32 v32, v39, v32
	v_add_f32_e32 v32, v72, v32
	v_add_f32_e32 v32, v73, v32
	v_add_f32_e32 v32, v84, v32
	v_add_f32_e32 v104, v89, v32
	v_mov_b32_e32 v105, v104
	v_cvt_pk_bf16_f32 v32, v90, v91
	v_cvt_pk_bf16_f32 v33, v88, v87
	v_cvt_pk_bf16_f32 v34, v86, v85
	v_cvt_pk_bf16_f32 v35, v82, v81
	s_nop 1
	v_permlane32_swap_b32_e32 v104, v105
	v_permlane32_swap_b32_e32 v32, v34
	v_permlane32_swap_b32_e32 v33, v35
	v_cvt_pk_bf16_f32 v74, v74, v75
	v_cvt_pk_bf16_f32 v75, v76, v77
	v_cvt_pk_bf16_f32 v76, v78, v79
	v_cvt_pk_bf16_f32 v77, v80, v83
	v_cvt_pk_bf16_f32 v78, v96, v97
	v_cvt_pk_bf16_f32 v79, v98, v99
	v_cvt_pk_bf16_f32 v80, v100, v101
	v_cvt_pk_bf16_f32 v81, v102, v103
	v_cvt_pk_bf16_f32 v36, v36, v37
	v_cvt_pk_bf16_f32 v37, v38, v39
	v_cvt_pk_bf16_f32 v38, v72, v73
	v_cvt_pk_bf16_f32 v39, v84, v89
	s_nop 0
	v_permlane32_swap_b32_e32 v74, v76
	v_permlane32_swap_b32_e32 v75, v77
	v_permlane32_swap_b32_e32 v78, v80
	v_permlane32_swap_b32_e32 v79, v81
	v_permlane32_swap_b32_e32 v36, v38
	v_permlane32_swap_b32_e32 v37, v39
	v_mad_i64_i32 v[72:73], s[20:21], s97, v237, v[134:135]
	v_mad_i64_i32 v[82:83], s[20:21], s97, v237, v[136:137]
	global_load_dwordx4 v[96:99], v[72:73], off offset:1024
	global_load_dwordx4 v[100:103], v[82:83], off offset:1280
	ds_read_b64_tr_b16 v[82:83], v156 offset:0
	ds_read_b64_tr_b16 v[84:85], v156 offset:0x400
	ds_read_b64_tr_b16 v[86:87], v156 offset:0x800
	ds_read_b64_tr_b16 v[88:89], v156 offset:0xc00
	ds_read_b64_tr_b16 v[90:91], v156 offset:0x1000
	ds_read_b64_tr_b16 v[92:93], v156 offset:0x1400
	ds_read_b64_tr_b16 v[106:107], v156 offset:0x1800
	ds_read_b64_tr_b16 v[108:109], v156 offset:0x1c00
	s_nop 0
	s_waitcnt lgkmcnt(6)
	v_mfma_f32_32x32x16_bf16 v[0:15], v[32:35], v[82:85], v[0:15]
	ds_read_b64_tr_b16 v[82:83], v156 offset:0x200
	ds_read_b64_tr_b16 v[84:85], v156 offset:0x600
	s_waitcnt lgkmcnt(6)
	v_mfma_f32_32x32x16_bf16 v[0:15], v[74:77], v[86:89], v[0:15]
	ds_read_b64_tr_b16 v[86:87], v156 offset:0xa00
	ds_read_b64_tr_b16 v[88:89], v156 offset:0xe00
	s_waitcnt lgkmcnt(6)
	v_mfma_f32_32x32x16_bf16 v[0:15], v[78:81], v[90:93], v[0:15]
	ds_read_b64_tr_b16 v[90:91], v156 offset:0x1200
	ds_read_b64_tr_b16 v[92:93], v156 offset:0x1600
	s_waitcnt lgkmcnt(6)
	v_mfma_f32_32x32x16_bf16 v[0:15], v[36:39], v[106:109], v[0:15]
	ds_read_b64_tr_b16 v[106:107], v156 offset:0x1a00
	ds_read_b64_tr_b16 v[108:109], v156 offset:0x1e00
	s_waitcnt lgkmcnt(6)
	v_mfma_f32_32x32x16_bf16 v[16:31], v[32:35], v[82:85], v[16:31]
	v_add_u32_e32 v82, s97, v151
	v_subrev_u32_e32 v34, 64, v82
	v_mov_b32_e32 v32, 0xf149f2ca
	v_cmp_gt_i32_e32 vcc, s94, v34
	v_mov_b32_e32 v33, 0xf149f2ca
	s_waitcnt lgkmcnt(4)
	v_mfma_f32_32x32x16_bf16 v[16:31], v[74:77], v[86:89], v[16:31]
	s_waitcnt lgkmcnt(2)
	v_mfma_f32_32x32x16_bf16 v[16:31], v[78:81], v[90:93], v[16:31]
	s_waitcnt lgkmcnt(0)
	v_mfma_f32_32x32x16_bf16 v[16:31], v[36:39], v[106:109], v[16:31]
	v_readfirstlane_b32 s100, v34
	v_readfirstlane_b32 s101, v145
	s_nop 0
	s_add_i32 s98, s100, 0x61
	s_cmp_ge_i32 s98, s101
	s_cbranch_scc0 .Lgq_slow_1
	s_add_i32 s98, s101, 0x41
	s_cmp_le_i32 s100, s98
	s_cbranch_scc0 .Lgq_slow_1
	s_add_i32 s98, s100, 64
	s_cmp_le_i32 s98, s94
	s_cbranch_scc0 .Lgq_slow_1
	v_mov_b32_e32 v33, v56
	v_mov_b32_e32 v32, v40
	v_mov_b32_e32 v34, v57
	v_mov_b32_e32 v83, v41
	v_mov_b32_e32 v35, v58
	v_mov_b32_e32 v84, v42
	v_mov_b32_e32 v36, v59
	v_mov_b32_e32 v85, v43
	v_mov_b32_e32 v37, v60
	v_mov_b32_e32 v86, v44
	v_mov_b32_e32 v38, v61
	v_mov_b32_e32 v87, v45
	v_mov_b32_e32 v39, v62
	v_mov_b32_e32 v88, v46
	v_mov_b32_e32 v40, v63
	v_mov_b32_e32 v89, v47
	v_mov_b32_e32 v41, v64
	v_mov_b32_e32 v90, v48
	v_mov_b32_e32 v42, v65
	v_mov_b32_e32 v91, v49
	v_mov_b32_e32 v43, v66
	v_mov_b32_e32 v92, v50
	v_mov_b32_e32 v44, v67
	v_mov_b32_e32 v93, v51
	v_mov_b32_e32 v45, v68
	v_mov_b32_e32 v94, v52
	v_mov_b32_e32 v46, v69
	v_mov_b32_e32 v95, v53
	v_mov_b32_e32 v47, v70
	v_mov_b32_e32 v106, v54
	v_mov_b32_e32 v48, v71
	v_mov_b32_e32 v107, v55
	s_branch .Lgq_end_1
; __device__ __forceinline__ int crow(int r, int hi) { return (r & 3) + 8 * (r >> 2) + 4 * hi; }
; template <bool GM>
; __device__ __forceinline__ void partialSM(f32x16& p0, f32x16& p1, bool mask, int kbase, int L, int qpos, int hi) {
;   if (mask) {
; #pragma unroll
;     for (int r = 0; r < 16; ++r) {
;       int k = kbase + crow(r, hi);
;       asm volatile("" : "+v"(k) : "v"(p0[r]));
;       bool ok = k < L;
;       if (GM) ok = ok && (k < 16 || abs(qpos - k) <= 128);
;       p0[r] = ok ? p0[r] : -1e30f;
.Lgq_slow_1:
	s_and_saveexec_b64 s[20:21], vcc
	s_cbranch_execz .LBB0_656
	v_cmp_gt_i32_e64 s[22:23], 16, v34
	v_cmp_lt_i32_e32 vcc, 15, v34
	s_and_saveexec_b64 s[72:73], vcc
	v_sub_u32_e32 v33, v145, v34
	v_sub_u32_e32 v35, 0, v33
	v_max_i32_e32 v33, v33, v35
	v_cmp_gt_u32_e32 vcc, s91, v33
	s_andn2_b64 s[22:23], s[22:23], exec
	s_and_b64 s[38:39], vcc, exec
	s_or_b64 s[22:23], s[22:23], s[38:39]
	s_or_b64 exec, exec, s[72:73]
	v_mov_b32_e32 v33, 0xf149f2ca
	s_and_saveexec_b64 s[72:73], s[22:23]
	v_mov_b32_e32 v33, v56
	s_or_b64 exec, exec, s[72:73]

; #define WAIT_V0() asm volatile("s_waitcnt vmcnt(0)" ::: "memory")
; #define SBAR() __builtin_amdgcn_sched_barrier(0)
; #define SWRITE(b) do { FRESH_COORDS(); \
;     if constexpr (!KDMA) { _Pragma("unroll") for (int i = 0; i < KC; ++i) *reinterpret_cast<bf16x8*>(shm + (b) * SHM_K + klo[i]) = ks[i]; } \
;     _Pragma("unroll") for (int i = 0; i < VC; ++i) *reinterpret_cast<bf16x8*>(shm + (b) * SHM_V + vlo[i]) = vs[i]; } while (0)
; #define QKT(P0, P1, BUF) qkt<DQK, QL>(P0, P1, shm + K_OFF + (BUF) * SHM_K, qr, qlds, kofs, negM)
;     ...
;     partialSM<GM>(pB0, pB1, NEEDMASK(kb), kb, L, qpos, hi);
;     __syncthreads(); WAIT_V0(); SWRITE(0);
;     __syncthreads();
;     SBAR();
;     if constexpr (ONEP) { finishSM(pB0, pB1, l_reg, pa0, pa1, pa2, pa3); SBAR(); QKT(pA0, pA1, 0); }
;     else { QKT(pA0, pA1, 0); finishSM(pB0, pB1, l_reg, pa0, pa1, pa2, pa3); }
;     SBAR();
;     if (j + 2 < NT) SLOAD(TKEY(j + 2), 1);
.Lgq_end_1:
	s_barrier
	s_waitcnt vmcnt(0)
	v_exp_f32_e32 v33, v33
	v_exp_f32_e32 v157, v34
	v_exp_f32_e32 v158, v35
	v_exp_f32_e32 v159, v36
	v_exp_f32_e32 v160, v37
	v_exp_f32_e32 v161, v38
	v_exp_f32_e32 v162, v39
	v_exp_f32_e32 v163, v40
	v_exp_f32_e32 v164, v41
	v_exp_f32_e32 v165, v42
	v_exp_f32_e32 v166, v43
	v_exp_f32_e32 v167, v44
	v_exp_f32_e32 v168, v45
	v_exp_f32_e32 v169, v46
	v_exp_f32_e32 v170, v47
	v_exp_f32_e32 v171, v48
	s_waitcnt vmcnt(1)
	ds_write_b128 v154, v[96:99] offset:32768
	s_waitcnt vmcnt(0)
	ds_write_b128 v153, v[100:103]
	s_waitcnt lgkmcnt(0)
	s_barrier
	ds_read_b128 v[34:37], v150 offset:32768
	ds_read_b128 v[108:111], v150 offset:36864
	v_mov_b64_e32 v[80:81], s[18:19]
	v_mov_b64_e32 v[78:79], s[16:17]
	v_mov_b64_e32 v[76:77], s[14:15]
	v_mov_b64_e32 v[74:75], s[12:13]
	v_mov_b64_e32 v[72:73], s[10:11]
	v_mov_b64_e32 v[70:71], s[8:9]
	v_mov_b64_e32 v[68:69], s[6:7]
	v_mov_b64_e32 v[66:67], s[4:5]
	v_exp_f32_e32 v32, v32
	s_waitcnt lgkmcnt(1)
	v_mfma_f32_32x32x16_bf16 v[50:65], v[34:37], v[124:127], v[66:81]
	s_waitcnt lgkmcnt(0)
	v_mfma_f32_32x32x16_bf16 v[34:49], v[108:111], v[124:127], v[66:81]
	s_nop 6
	ds_read_b128 v[66:69], v148 offset:32768
	ds_read_b128 v[70:73], v148 offset:36864
	v_exp_f32_e32 v80, v87
	v_exp_f32_e32 v81, v88
	v_exp_f32_e32 v87, v92
	v_exp_f32_e32 v88, v93
	v_exp_f32_e32 v92, v107
	s_waitcnt lgkmcnt(1)
	v_mfma_f32_32x32x16_bf16 v[50:65], v[66:69], v[120:123], v[50:65]
	s_waitcnt lgkmcnt(0)
	v_mfma_f32_32x32x16_bf16 v[34:49], v[70:73], v[120:123], v[34:49]
	ds_read_b128 v[66:69], v147 offset:32768
	ds_read_b128 v[70:73], v147 offset:36864
	s_waitcnt lgkmcnt(1)
	v_mfma_f32_32x32x16_bf16 v[50:65], v[66:69], v[116:119], v[50:65]
	s_waitcnt lgkmcnt(0)
	v_mfma_f32_32x32x16_bf16 v[34:49], v[70:73], v[116:119], v[34:49]
	ds_read_b128 v[66:69], v146 offset:32768
	ds_read_b128 v[70:73], v146 offset:36864
	s_waitcnt lgkmcnt(1)
	v_mfma_f32_32x32x16_bf16 v[50:65], v[66:69], v[112:115], v[50:65]
	v_add_f32_e32 v66, 0, v33
	v_add_f32_e32 v66, v66, v157
	v_add_f32_e32 v66, v66, v158
	v_add_f32_e32 v66, v66, v159
	v_add_f32_e32 v66, v66, v160
	v_add_f32_e32 v66, v66, v161
	v_add_f32_e32 v66, v66, v162
	v_add_f32_e32 v66, v66, v163
	v_add_f32_e32 v66, v66, v164
	v_add_f32_e32 v66, v66, v165
	v_add_f32_e32 v66, v66, v166
	v_add_f32_e32 v66, v66, v167
	v_add_f32_e32 v66, v66, v168
	s_waitcnt lgkmcnt(0)
	v_mfma_f32_32x32x16_bf16 v[34:49], v[70:73], v[112:115], v[34:49]
	v_exp_f32_e32 v70, v83
	v_add_f32_e32 v66, v66, v169
	v_exp_f32_e32 v71, v84
	v_add_f32_e32 v66, v66, v170
	v_exp_f32_e32 v72, v85
	v_add_f32_e32 v66, v66, v171
	v_exp_f32_e32 v73, v86
	v_add_f32_e32 v66, v32, v66
	v_add_f32_e32 v66, v70, v66
	v_add_f32_e32 v66, v71, v66
	v_exp_f32_e32 v84, v89
	v_add_f32_e32 v66, v72, v66
	v_exp_f32_e32 v85, v90
	v_add_f32_e32 v66, v73, v66
	v_exp_f32_e32 v86, v91
	v_add_f32_e32 v66, v80, v66
	v_add_f32_e32 v66, v81, v66
	v_add_f32_e32 v66, v84, v66
	v_exp_f32_e32 v89, v94
	v_add_f32_e32 v66, v85, v66
	v_exp_f32_e32 v90, v95
	v_add_f32_e32 v66, v86, v66
	v_exp_f32_e32 v91, v106
	v_add_f32_e32 v66, v87, v66
	v_add_f32_e32 v66, v88, v66
	v_add_f32_e32 v66, v89, v66
	v_add_f32_e32 v66, v90, v66
	v_add_f32_e32 v66, v91, v66
	v_add_f32_e32 v83, v66, v92
	v_mov_b32_e32 v106, v83
	v_cvt_pk_bf16_f32 v66, v33, v157
	v_cvt_pk_bf16_f32 v67, v158, v159
	v_cvt_pk_bf16_f32 v68, v160, v161
	v_cvt_pk_bf16_f32 v69, v162, v163
	v_cvt_pk_bf16_f32 v74, v164, v165
	v_cvt_pk_bf16_f32 v75, v166, v167
	v_cvt_pk_bf16_f32 v76, v168, v169
	v_cvt_pk_bf16_f32 v77, v170, v171
	v_cvt_pk_bf16_f32 v78, v32, v70
	v_cvt_pk_bf16_f32 v79, v71, v72
	v_cvt_pk_bf16_f32 v80, v73, v80
	v_cvt_pk_bf16_f32 v81, v81, v84
	v_cvt_pk_bf16_f32 v70, v85, v86
	v_cvt_pk_bf16_f32 v71, v87, v88
	v_cvt_pk_bf16_f32 v72, v89, v90
	v_cvt_pk_bf16_f32 v73, v91, v92
	s_nop 1
	v_permlane32_swap_b32_e32 v83, v106
	v_permlane32_swap_b32_e32 v66, v68
	v_permlane32_swap_b32_e32 v67, v69
	v_permlane32_swap_b32_e32 v74, v76
	v_permlane32_swap_b32_e32 v75, v77
	v_permlane32_swap_b32_e32 v78, v80
	v_permlane32_swap_b32_e32 v79, v81
	v_permlane32_swap_b32_e32 v70, v72
	v_permlane32_swap_b32_e32 v71, v73
	s_cmp_lt_i32 s87, s89
	s_cselect_b64 s[72:73], -1, 0
	s_cmp_ge_i32 s87, s89
	s_cbranch_scc1 .LBB0_844
	s_add_i32 s3, s97, 64
	v_mad_i64_i32 v[32:33], s[20:21], s3, v237, v[134:135]
	v_mad_i64_i32 v[84:85], s[20:21], s3, v237, v[136:137]
	global_load_dwordx4 v[96:99], v[32:33], off offset:1024
	global_load_dwordx4 v[100:103], v[84:85], off offset:1280
; __device__ __forceinline__ int crow(int r, int hi) { return (r & 3) + 8 * (r >> 2) + 4 * hi; }
; template <bool GM>
; __device__ __forceinline__ void partialSM(f32x16& p0, f32x16& p1, bool mask, int kbase, int L, int qpos, int hi) {
;   if (mask) {
; #pragma unroll
;     for (int r = 0; r < 16; ++r) {
;       int k = kbase + crow(r, hi);
;       asm volatile("" : "+v"(k) : "v"(p0[r]));
;       bool ok = k < L;
;       if (GM) ok = ok && (k < 16 || abs(qpos - k) <= 128);
;       p0[r] = ok ? p0[r] : -1e30f;
;       int k2 = k + 32;
;       asm volatile("" : "+v"(k2) : "v"(p1[r]));
;       bool ok2 = k2 < L;
;       if (GM) ok2 = ok2 && (k2 < 16 || abs(qpos - k2) <= 128);
;       p1[r] = ok2 ? p1[r] : -1e30f;
;     }
;   }
;     ...
;     pv_all<NCB>(o, vb0 + SHM_V, pa0, pa1, pa2, pa3);
;     kb = TKEY(j + 1);
;     partialSM<GM>(pA0, pA1, NEEDMASK(kb), kb, L, qpos, hi);
.LBB0_844:
	ds_read_b64_tr_b16 v[84:85], v149 offset:0
	ds_read_b64_tr_b16 v[86:87], v149 offset:0x400
	ds_read_b64_tr_b16 v[88:89], v149 offset:0x800
	ds_read_b64_tr_b16 v[90:91], v149 offset:0xc00
	ds_read_b64_tr_b16 v[92:93], v149 offset:0x1000
	ds_read_b64_tr_b16 v[94:95], v149 offset:0x1400
	ds_read_b64_tr_b16 v[108:109], v149 offset:0x1800
	ds_read_b64_tr_b16 v[110:111], v149 offset:0x1c00
	s_nop 0
	s_waitcnt lgkmcnt(6)
	v_mfma_f32_32x32x16_bf16 v[0:15], v[66:69], v[84:87], v[0:15]
	ds_read_b64_tr_b16 v[84:85], v149 offset:0x200
	ds_read_b64_tr_b16 v[86:87], v149 offset:0x600
	s_waitcnt lgkmcnt(6)
	v_mfma_f32_32x32x16_bf16 v[0:15], v[74:77], v[88:91], v[0:15]
	ds_read_b64_tr_b16 v[88:89], v149 offset:0xa00
	ds_read_b64_tr_b16 v[90:91], v149 offset:0xe00
	s_waitcnt lgkmcnt(6)
	v_mfma_f32_32x32x16_bf16 v[0:15], v[78:81], v[92:95], v[0:15]
	ds_read_b64_tr_b16 v[92:93], v149 offset:0x1200
	ds_read_b64_tr_b16 v[94:95], v149 offset:0x1600
	s_waitcnt lgkmcnt(6)
	v_mfma_f32_32x32x16_bf16 v[0:15], v[70:73], v[108:111], v[0:15]
	ds_read_b64_tr_b16 v[108:109], v149 offset:0x1a00
	ds_read_b64_tr_b16 v[110:111], v149 offset:0x1e00
	s_waitcnt lgkmcnt(6)
	v_mfma_f32_32x32x16_bf16 v[16:31], v[66:69], v[84:87], v[16:31]
	v_mov_b32_e32 v33, v82
	v_mov_b32_e32 v32, 0xf149f2ca
	v_cmp_gt_i32_e32 vcc, s94, v33
	v_mov_b32_e32 v66, 0xf149f2ca
	s_waitcnt lgkmcnt(4)
	v_mfma_f32_32x32x16_bf16 v[16:31], v[74:77], v[88:91], v[16:31]
	s_waitcnt lgkmcnt(2)
	v_mfma_f32_32x32x16_bf16 v[16:31], v[78:81], v[92:95], v[16:31]
	s_waitcnt lgkmcnt(0)
	v_mfma_f32_32x32x16_bf16 v[16:31], v[70:73], v[108:111], v[16:31]
	v_readfirstlane_b32 s100, v33
	v_readfirstlane_b32 s101, v145
	s_nop 0
	s_add_i32 s98, s100, 0x61
	s_cmp_ge_i32 s98, s101
	s_cbranch_scc0 .Lgq_slow_2
	s_add_i32 s98, s101, 0x41
	s_cmp_le_i32 s100, s98
	s_cbranch_scc0 .Lgq_slow_2
	s_add_i32 s98, s100, 64
	s_cmp_le_i32 s98, s94
	s_cbranch_scc0 .Lgq_slow_2
	v_mov_b32_e32 v66, v50
	v_mov_b32_e32 v32, v34
	v_mov_b32_e32 v50, v51
	v_mov_b32_e32 v33, v35
	v_mov_b32_e32 v51, v52
	v_mov_b32_e32 v34, v36
	v_mov_b32_e32 v52, v53
	v_mov_b32_e32 v35, v37
	v_mov_b32_e32 v53, v54
	v_mov_b32_e32 v36, v38
	v_mov_b32_e32 v54, v55
	v_mov_b32_e32 v37, v39
	v_mov_b32_e32 v55, v56
	v_mov_b32_e32 v38, v40
	v_mov_b32_e32 v40, v57
	v_mov_b32_e32 v39, v41
	v_mov_b32_e32 v41, v58
	v_mov_b32_e32 v72, v42
	v_mov_b32_e32 v42, v59
	v_mov_b32_e32 v73, v43
	v_mov_b32_e32 v43, v60
	v_mov_b32_e32 v84, v44
	v_mov_b32_e32 v44, v61
	v_mov_b32_e32 v89, v45
	v_mov_b32_e32 v45, v62
	v_mov_b32_e32 v92, v46
	v_mov_b32_e32 v46, v63
	v_mov_b32_e32 v93, v47
	v_mov_b32_e32 v47, v64
	v_mov_b32_e32 v94, v48
	v_mov_b32_e32 v48, v65
	v_mov_b32_e32 v95, v49
	s_branch .Lgq_end_2
.Lgq_slow_2:
	s_and_saveexec_b64 s[20:21], vcc
	s_cbranch_execz .LBB0_850
	v_cmp_gt_i32_e64 s[22:23], 16, v33
	v_cmp_lt_i32_e32 vcc, 15, v33
	s_and_saveexec_b64 s[74:75], vcc
	v_sub_u32_e32 v66, v145, v33
	v_sub_u32_e32 v67, 0, v66
	v_max_i32_e32 v66, v66, v67
	v_cmp_gt_u32_e32 vcc, s91, v66
	s_andn2_b64 s[22:23], s[22:23], exec
	s_and_b64 s[38:39], vcc, exec
	s_or_b64 s[22:23], s[22:23], s[38:39]
	s_or_b64 exec, exec, s[74:75]
	v_mov_b32_e32 v66, 0xf149f2ca
	s_and_saveexec_b64 s[74:75], s[22:23]
	v_mov_b32_e32 v66, v50
	s_or_b64 exec, exec, s[74:75]

; #define WAIT_V0() asm volatile("s_waitcnt vmcnt(0)" ::: "memory")
; #define SWRITE(b) do { FRESH_COORDS(); \
;     if constexpr (!KDMA) { _Pragma("unroll") for (int i = 0; i < KC; ++i) *reinterpret_cast<bf16x8*>(shm + (b) * SHM_K + klo[i]) = ks[i]; } \
;     _Pragma("unroll") for (int i = 0; i < VC; ++i) *reinterpret_cast<bf16x8*>(shm + (b) * SHM_V + vlo[i]) = vs[i]; } while (0)
;     ...
;     __syncthreads();
;     if (j + 2 < NT) { WAIT_V0(); SWRITE(1); }
;     __syncthreads();
.Lgq_end_2:
	s_andn2_b64 vcc, exec, s[72:73]
	s_barrier
	s_cbranch_vccnz .LBB0_1038
	s_waitcnt vmcnt(0)
	s_waitcnt vmcnt(1)
	ds_write_b128 v154, v[96:99] offset:40960
	s_waitcnt vmcnt(0)
	ds_write_b128 v153, v[100:103] offset:8192
